# hand-written bias_task now used at all three call sites (prep1, ret phase, ffn_out phase)
# speedup vs baseline: 1.0157x; 1.0058x over previous
.LBB0_102:
	s_or_b32 s28, s33, 0x400
	s_branch .Lbias_task
.Lbias_ret1:
	s_branch .LBB0_87
.LBB0_104:
	s_cbranch_execnz .LBB0_87
	s_branch .LBB0_102

.Lbias_task:
	v_writelane_b32 v255, s40, 42
	v_writelane_b32 v255, s41, 43
	v_writelane_b32 v255, s42, 44
	v_writelane_b32 v255, s43, 45
	v_writelane_b32 v255, s44, 46
	v_writelane_b32 v255, s45, 47
	v_writelane_b32 v255, s46, 48
	v_writelane_b32 v255, s47, 49
	v_writelane_b32 v255, s48, 50
	v_writelane_b32 v255, s49, 51
	v_writelane_b32 v255, s50, 52
	v_writelane_b32 v255, s51, 53
	v_writelane_b32 v255, s52, 54
	v_writelane_b32 v255, s53, 55
	v_writelane_b32 v255, s54, 56
	v_writelane_b32 v255, s55, 57
	s_mov_b64 s[50:51], exec
	v_mul_u32_u24_e32 v0, 0xc0, v228
	ds_write_b128 v0, v[128:131] offset:0
	ds_write_b128 v0, v[132:135] offset:16
	ds_write_b128 v0, v[136:139] offset:32
	ds_write_b128 v0, v[140:143] offset:48
	ds_write_b128 v0, v[144:147] offset:64
	ds_write_b128 v0, v[148:151] offset:80
	ds_write_b128 v0, v[152:155] offset:96
	ds_write_b128 v0, v[156:159] offset:112
	ds_write_b128 v0, v[160:163] offset:128
	ds_write_b128 v0, v[164:167] offset:144
	ds_write_b128 v0, v[168:171] offset:160
	ds_write_b128 v0, v[172:175] offset:176
	s_and_b32 s54, s28, 0xff
	s_bfe_u32 s47, s28, 0x10008
	s_bfe_u32 s48, s28, 0x10009
	s_lshr_b32 s49, s28, 10
	s_movk_i32 s55, 0x58
	s_cmp_eq_u32 s49, 2
	s_cbranch_scc0 .Lbias_nt
	s_movk_i32 s55, 0xb0
.Lbias_nt:
	v_readlane_b32 s40, v255, 7
	v_readlane_b32 s41, v255, 8
	s_mul_i32 s52, s47, 0x1e000
	s_mul_i32 s53, s48, 0x3000
	s_add_u32 s52, s52, s53
	s_nop 1
	s_add_u32 s40, s40, s52
	s_addc_u32 s41, s41, 0
	s_cmp_eq_u32 s48, 0
	s_cbranch_scc1 .Lbias_w0
	v_readlane_b32 s42, v254, 63
	v_readlane_b32 s43, v255, 0
	s_mul_i32 s52, s47, 0xb00000
	s_mov_b32 s44, s10
	s_mov_b32 s45, s11
	s_mul_i32 s53, s47, 0x1b800
	s_movk_i32 s46, 0x5800
	s_branch .Lbias_w1

.Lbias_again:
	v_and_b32_e32 v160, 63, v229
	v_lshrrev_b32_e32 v161, 6, v229
	v_lshlrev_b32_e32 v162, 6, v160
	v_add_u32_e32 v163, 0x6000, v162
	v_add_u32_e32 v164, 0xc000, v162
	v_add_u32_e32 v165, 0x12000, v162
	v_add_u32_e32 v166, 0x18000, v162
	v_lshlrev_b32_e32 v167, 5, v160
	v_lshl_add_u32 v167, v161, 14, v167
	s_lshl_b32 s52, s54, 16
	v_add_u32_e32 v167, s52, v167
	v_add_u32_e32 v168, 0x1000, v167
	v_add_u32_e32 v169, 0x2000, v167
	v_add_u32_e32 v170, 0x3000, v167
	s_nop 4
	global_load_dwordx4 v[0:3], v162, s[40:41]
	global_load_dwordx4 v[4:7], v162, s[40:41] offset:16
	global_load_dwordx4 v[8:11], v162, s[40:41] offset:32
	global_load_dwordx4 v[12:15], v162, s[40:41] offset:48
	global_load_dwordx4 v[16:19], v163, s[40:41]
	global_load_dwordx4 v[20:23], v163, s[40:41] offset:16
	global_load_dwordx4 v[24:27], v163, s[40:41] offset:32
	global_load_dwordx4 v[28:31], v163, s[40:41] offset:48
	global_load_dwordx4 v[32:35], v164, s[40:41]
	global_load_dwordx4 v[36:39], v164, s[40:41] offset:16
	global_load_dwordx4 v[40:43], v164, s[40:41] offset:32
	global_load_dwordx4 v[44:47], v164, s[40:41] offset:48
	global_load_dwordx4 v[48:51], v165, s[40:41]
	global_load_dwordx4 v[52:55], v165, s[40:41] offset:16
	global_load_dwordx4 v[56:59], v165, s[40:41] offset:32
	global_load_dwordx4 v[60:63], v165, s[40:41] offset:48
	global_load_dwordx4 v[64:67], v166, s[40:41]
	global_load_dwordx4 v[68:71], v166, s[40:41] offset:16
	global_load_dwordx4 v[72:75], v166, s[40:41] offset:32
	global_load_dwordx4 v[76:79], v166, s[40:41] offset:48
	global_load_dwordx4 v[80:83], v167, s[42:43]
	global_load_dwordx4 v[84:87], v167, s[42:43] offset:16
	global_load_dwordx4 v[112:115], v169, s[42:43]
	global_load_dwordx4 v[116:119], v169, s[42:43] offset:16
	global_load_dwordx4 v[88:91], v167, s[42:43] offset:2048
	global_load_dwordx4 v[92:95], v167, s[42:43] offset:2064
	global_load_dwordx4 v[120:123], v169, s[42:43] offset:2048
	global_load_dwordx4 v[124:127], v169, s[42:43] offset:2064
	global_load_dwordx4 v[96:99], v168, s[42:43]
	global_load_dwordx4 v[100:103], v168, s[42:43] offset:16
	global_load_dwordx4 v[128:131], v170, s[42:43]
	global_load_dwordx4 v[132:135], v170, s[42:43] offset:16
	global_load_dwordx4 v[104:107], v168, s[42:43] offset:2048
	global_load_dwordx4 v[108:111], v168, s[42:43] offset:2064
	global_load_dwordx4 v[136:139], v170, s[42:43] offset:2048
	global_load_dwordx4 v[140:143], v170, s[42:43] offset:2064
	s_waitcnt vmcnt(12)
	v_lshlrev_b32_e32 v144, 16, v80
	v_and_b32_e32 v145, 0xffff0000, v80
	v_lshlrev_b32_e32 v146, 16, v81
	v_and_b32_e32 v147, 0xffff0000, v81
	v_lshlrev_b32_e32 v148, 16, v82
	v_and_b32_e32 v149, 0xffff0000, v82
	v_lshlrev_b32_e32 v150, 16, v83
	v_and_b32_e32 v151, 0xffff0000, v83
	v_lshlrev_b32_e32 v152, 16, v84
	v_and_b32_e32 v153, 0xffff0000, v84
	v_lshlrev_b32_e32 v154, 16, v85
	v_and_b32_e32 v155, 0xffff0000, v85
	v_lshlrev_b32_e32 v156, 16, v86
	v_and_b32_e32 v157, 0xffff0000, v86
	v_lshlrev_b32_e32 v158, 16, v87
	v_and_b32_e32 v159, 0xffff0000, v87
	v_pk_mul_f32 v[160:161], v[0:1], v[144:145]
	v_pk_mul_f32 v[162:163], v[8:9], v[152:153]
	v_pk_fma_f32 v[160:161], v[2:3], v[146:147], v[160:161]
	v_pk_fma_f32 v[162:163], v[10:11], v[154:155], v[162:163]
	v_pk_fma_f32 v[160:161], v[4:5], v[148:149], v[160:161]
	v_pk_fma_f32 v[162:163], v[12:13], v[156:157], v[162:163]
	v_pk_fma_f32 v[160:161], v[6:7], v[150:151], v[160:161]
	v_pk_fma_f32 v[162:163], v[14:15], v[158:159], v[162:163]
	v_pk_add_f32 v[160:161], v[160:161], v[162:163]
	s_nop 0
	v_add_f32_e32 v164, v160, v161
	v_pk_mul_f32 v[160:161], v[16:17], v[144:145]
	v_pk_mul_f32 v[162:163], v[24:25], v[152:153]
	v_pk_fma_f32 v[160:161], v[18:19], v[146:147], v[160:161]
	v_pk_fma_f32 v[162:163], v[26:27], v[154:155], v[162:163]
	v_pk_fma_f32 v[160:161], v[20:21], v[148:149], v[160:161]
	v_pk_fma_f32 v[162:163], v[28:29], v[156:157], v[162:163]
	v_pk_fma_f32 v[160:161], v[22:23], v[150:151], v[160:161]
	v_pk_fma_f32 v[162:163], v[30:31], v[158:159], v[162:163]
	v_pk_add_f32 v[160:161], v[160:161], v[162:163]
	s_nop 0
	v_add_f32_e32 v165, v160, v161
	v_pk_mul_f32 v[160:161], v[32:33], v[144:145]
	v_pk_mul_f32 v[162:163], v[40:41], v[152:153]
	v_pk_fma_f32 v[160:161], v[34:35], v[146:147], v[160:161]
	v_pk_fma_f32 v[162:163], v[42:43], v[154:155], v[162:163]
	v_pk_fma_f32 v[160:161], v[36:37], v[148:149], v[160:161]
	v_pk_fma_f32 v[162:163], v[44:45], v[156:157], v[162:163]
	v_pk_fma_f32 v[160:161], v[38:39], v[150:151], v[160:161]
	v_pk_fma_f32 v[162:163], v[46:47], v[158:159], v[162:163]
	v_pk_add_f32 v[160:161], v[160:161], v[162:163]
	s_nop 0
	v_add_f32_e32 v166, v160, v161
	v_pk_mul_f32 v[160:161], v[48:49], v[144:145]
	v_pk_mul_f32 v[162:163], v[56:57], v[152:153]
	v_pk_fma_f32 v[160:161], v[50:51], v[146:147], v[160:161]
	v_pk_fma_f32 v[162:163], v[58:59], v[154:155], v[162:163]
	v_pk_fma_f32 v[160:161], v[52:53], v[148:149], v[160:161]
	v_pk_fma_f32 v[162:163], v[60:61], v[156:157], v[162:163]
	v_pk_fma_f32 v[160:161], v[54:55], v[150:151], v[160:161]
	v_pk_fma_f32 v[162:163], v[62:63], v[158:159], v[162:163]
	v_pk_add_f32 v[160:161], v[160:161], v[162:163]
	s_nop 0
	v_add_f32_e32 v167, v160, v161
	v_pk_mul_f32 v[160:161], v[64:65], v[144:145]
	v_pk_mul_f32 v[162:163], v[72:73], v[152:153]
	v_pk_fma_f32 v[160:161], v[66:67], v[146:147], v[160:161]
	v_pk_fma_f32 v[162:163], v[74:75], v[154:155], v[162:163]
	v_pk_fma_f32 v[160:161], v[68:69], v[148:149], v[160:161]
	v_pk_fma_f32 v[162:163], v[76:77], v[156:157], v[162:163]
	v_pk_fma_f32 v[160:161], v[70:71], v[150:151], v[160:161]
	v_pk_fma_f32 v[162:163], v[78:79], v[158:159], v[162:163]
	v_pk_add_f32 v[160:161], v[160:161], v[162:163]
	s_nop 0
	v_add_f32_e32 v168, v160, v161
	v_lshlrev_b32_e32 v144, 16, v112
	v_and_b32_e32 v145, 0xffff0000, v112
	v_lshlrev_b32_e32 v146, 16, v113
	v_and_b32_e32 v147, 0xffff0000, v113
	v_lshlrev_b32_e32 v148, 16, v114
	v_and_b32_e32 v149, 0xffff0000, v114
	v_lshlrev_b32_e32 v150, 16, v115
	v_and_b32_e32 v151, 0xffff0000, v115
	v_lshlrev_b32_e32 v152, 16, v116
	v_and_b32_e32 v153, 0xffff0000, v116
	v_lshlrev_b32_e32 v154, 16, v117
	v_and_b32_e32 v155, 0xffff0000, v117
	v_lshlrev_b32_e32 v156, 16, v118
	v_and_b32_e32 v157, 0xffff0000, v118
	v_lshlrev_b32_e32 v158, 16, v119
	v_and_b32_e32 v159, 0xffff0000, v119
	v_pk_mul_f32 v[160:161], v[0:1], v[144:145]
	v_pk_mul_f32 v[162:163], v[8:9], v[152:153]
	v_pk_fma_f32 v[160:161], v[2:3], v[146:147], v[160:161]
	v_pk_fma_f32 v[162:163], v[10:11], v[154:155], v[162:163]
	v_pk_fma_f32 v[160:161], v[4:5], v[148:149], v[160:161]
	v_pk_fma_f32 v[162:163], v[12:13], v[156:157], v[162:163]
	v_pk_fma_f32 v[160:161], v[6:7], v[150:151], v[160:161]
	v_pk_fma_f32 v[162:163], v[14:15], v[158:159], v[162:163]
	v_pk_add_f32 v[160:161], v[160:161], v[162:163]
	s_nop 0
	v_add_f32_e32 v169, v160, v161
	v_pk_mul_f32 v[160:161], v[16:17], v[144:145]
	v_pk_mul_f32 v[162:163], v[24:25], v[152:153]
	v_pk_fma_f32 v[160:161], v[18:19], v[146:147], v[160:161]
	v_pk_fma_f32 v[162:163], v[26:27], v[154:155], v[162:163]
	v_pk_fma_f32 v[160:161], v[20:21], v[148:149], v[160:161]
	v_pk_fma_f32 v[162:163], v[28:29], v[156:157], v[162:163]
	v_pk_fma_f32 v[160:161], v[22:23], v[150:151], v[160:161]
	v_pk_fma_f32 v[162:163], v[30:31], v[158:159], v[162:163]
	v_pk_add_f32 v[160:161], v[160:161], v[162:163]
	s_nop 0
	v_add_f32_e32 v170, v160, v161
	v_pk_mul_f32 v[160:161], v[32:33], v[144:145]
	v_pk_mul_f32 v[162:163], v[40:41], v[152:153]
	v_pk_fma_f32 v[160:161], v[34:35], v[146:147], v[160:161]
	v_pk_fma_f32 v[162:163], v[42:43], v[154:155], v[162:163]
	v_pk_fma_f32 v[160:161], v[36:37], v[148:149], v[160:161]
	v_pk_fma_f32 v[162:163], v[44:45], v[156:157], v[162:163]
	v_pk_fma_f32 v[160:161], v[38:39], v[150:151], v[160:161]
	v_pk_fma_f32 v[162:163], v[46:47], v[158:159], v[162:163]
	v_pk_add_f32 v[160:161], v[160:161], v[162:163]
	s_nop 0
	v_add_f32_e32 v171, v160, v161
	v_pk_mul_f32 v[160:161], v[48:49], v[144:145]
	v_pk_mul_f32 v[162:163], v[56:57], v[152:153]
	v_pk_fma_f32 v[160:161], v[50:51], v[146:147], v[160:161]
	v_pk_fma_f32 v[162:163], v[58:59], v[154:155], v[162:163]
	v_pk_fma_f32 v[160:161], v[52:53], v[148:149], v[160:161]
	v_pk_fma_f32 v[162:163], v[60:61], v[156:157], v[162:163]
	v_pk_fma_f32 v[160:161], v[54:55], v[150:151], v[160:161]
	v_pk_fma_f32 v[162:163], v[62:63], v[158:159], v[162:163]
	v_pk_add_f32 v[160:161], v[160:161], v[162:163]
	s_nop 0
	v_add_f32_e32 v172, v160, v161
	v_pk_mul_f32 v[160:161], v[64:65], v[144:145]
	v_pk_mul_f32 v[162:163], v[72:73], v[152:153]
	v_pk_fma_f32 v[160:161], v[66:67], v[146:147], v[160:161]
	v_pk_fma_f32 v[162:163], v[74:75], v[154:155], v[162:163]
	v_pk_fma_f32 v[160:161], v[68:69], v[148:149], v[160:161]
	v_pk_fma_f32 v[162:163], v[76:77], v[156:157], v[162:163]
	v_pk_fma_f32 v[160:161], v[70:71], v[150:151], v[160:161]
	v_pk_fma_f32 v[162:163], v[78:79], v[158:159], v[162:163]
	v_pk_add_f32 v[160:161], v[160:161], v[162:163]
	s_nop 0
	v_add_f32_e32 v173, v160, v161
	s_nop 1
	v_permlane32_swap_b32_e32 v164, v169
	v_permlane32_swap_b32_e32 v165, v170
	v_permlane32_swap_b32_e32 v166, v171
	v_permlane32_swap_b32_e32 v167, v172
	v_permlane32_swap_b32_e32 v168, v173
	s_nop 1
	v_add_f32_e32 v80, v164, v169
	v_add_f32_e32 v81, v165, v170
	v_add_f32_e32 v82, v166, v171
	v_add_f32_e32 v83, v167, v172
	v_add_f32_e32 v84, v168, v173
	s_waitcnt vmcnt(8)
	v_lshlrev_b32_e32 v144, 16, v88
	v_and_b32_e32 v145, 0xffff0000, v88
	v_lshlrev_b32_e32 v146, 16, v89
	v_and_b32_e32 v147, 0xffff0000, v89
	v_lshlrev_b32_e32 v148, 16, v90
	v_and_b32_e32 v149, 0xffff0000, v90
	v_lshlrev_b32_e32 v150, 16, v91
	v_and_b32_e32 v151, 0xffff0000, v91
	v_lshlrev_b32_e32 v152, 16, v92
	v_and_b32_e32 v153, 0xffff0000, v92
	v_lshlrev_b32_e32 v154, 16, v93
	v_and_b32_e32 v155, 0xffff0000, v93
	v_lshlrev_b32_e32 v156, 16, v94
	v_and_b32_e32 v157, 0xffff0000, v94
	v_lshlrev_b32_e32 v158, 16, v95
	v_and_b32_e32 v159, 0xffff0000, v95
	v_pk_mul_f32 v[160:161], v[0:1], v[144:145]
	v_pk_mul_f32 v[162:163], v[8:9], v[152:153]
	v_pk_fma_f32 v[160:161], v[2:3], v[146:147], v[160:161]
	v_pk_fma_f32 v[162:163], v[10:11], v[154:155], v[162:163]
	v_pk_fma_f32 v[160:161], v[4:5], v[148:149], v[160:161]
	v_pk_fma_f32 v[162:163], v[12:13], v[156:157], v[162:163]
	v_pk_fma_f32 v[160:161], v[6:7], v[150:151], v[160:161]
	v_pk_fma_f32 v[162:163], v[14:15], v[158:159], v[162:163]
	v_pk_add_f32 v[160:161], v[160:161], v[162:163]
	s_nop 0
	v_add_f32_e32 v164, v160, v161
	v_pk_mul_f32 v[160:161], v[16:17], v[144:145]
	v_pk_mul_f32 v[162:163], v[24:25], v[152:153]
	v_pk_fma_f32 v[160:161], v[18:19], v[146:147], v[160:161]
	v_pk_fma_f32 v[162:163], v[26:27], v[154:155], v[162:163]
	v_pk_fma_f32 v[160:161], v[20:21], v[148:149], v[160:161]
	v_pk_fma_f32 v[162:163], v[28:29], v[156:157], v[162:163]
	v_pk_fma_f32 v[160:161], v[22:23], v[150:151], v[160:161]
	v_pk_fma_f32 v[162:163], v[30:31], v[158:159], v[162:163]
	v_pk_add_f32 v[160:161], v[160:161], v[162:163]
	s_nop 0
	v_add_f32_e32 v165, v160, v161
	v_pk_mul_f32 v[160:161], v[32:33], v[144:145]
	v_pk_mul_f32 v[162:163], v[40:41], v[152:153]
	v_pk_fma_f32 v[160:161], v[34:35], v[146:147], v[160:161]
	v_pk_fma_f32 v[162:163], v[42:43], v[154:155], v[162:163]
	v_pk_fma_f32 v[160:161], v[36:37], v[148:149], v[160:161]
	v_pk_fma_f32 v[162:163], v[44:45], v[156:157], v[162:163]
	v_pk_fma_f32 v[160:161], v[38:39], v[150:151], v[160:161]
	v_pk_fma_f32 v[162:163], v[46:47], v[158:159], v[162:163]
	v_pk_add_f32 v[160:161], v[160:161], v[162:163]
	s_nop 0
	v_add_f32_e32 v166, v160, v161
	v_pk_mul_f32 v[160:161], v[48:49], v[144:145]
	v_pk_mul_f32 v[162:163], v[56:57], v[152:153]
	v_pk_fma_f32 v[160:161], v[50:51], v[146:147], v[160:161]
	v_pk_fma_f32 v[162:163], v[58:59], v[154:155], v[162:163]
	v_pk_fma_f32 v[160:161], v[52:53], v[148:149], v[160:161]
	v_pk_fma_f32 v[162:163], v[60:61], v[156:157], v[162:163]
	v_pk_fma_f32 v[160:161], v[54:55], v[150:151], v[160:161]
	v_pk_fma_f32 v[162:163], v[62:63], v[158:159], v[162:163]
	v_pk_add_f32 v[160:161], v[160:161], v[162:163]
	s_nop 0
	v_add_f32_e32 v167, v160, v161
	v_pk_mul_f32 v[160:161], v[64:65], v[144:145]
	v_pk_mul_f32 v[162:163], v[72:73], v[152:153]
	v_pk_fma_f32 v[160:161], v[66:67], v[146:147], v[160:161]
	v_pk_fma_f32 v[162:163], v[74:75], v[154:155], v[162:163]
	v_pk_fma_f32 v[160:161], v[68:69], v[148:149], v[160:161]
	v_pk_fma_f32 v[162:163], v[76:77], v[156:157], v[162:163]
	v_pk_fma_f32 v[160:161], v[70:71], v[150:151], v[160:161]
	v_pk_fma_f32 v[162:163], v[78:79], v[158:159], v[162:163]
	v_pk_add_f32 v[160:161], v[160:161], v[162:163]
	s_nop 0
	v_add_f32_e32 v168, v160, v161
	v_lshlrev_b32_e32 v144, 16, v120
	v_and_b32_e32 v145, 0xffff0000, v120
	v_lshlrev_b32_e32 v146, 16, v121
	v_and_b32_e32 v147, 0xffff0000, v121
	v_lshlrev_b32_e32 v148, 16, v122
	v_and_b32_e32 v149, 0xffff0000, v122
	v_lshlrev_b32_e32 v150, 16, v123
	v_and_b32_e32 v151, 0xffff0000, v123
	v_lshlrev_b32_e32 v152, 16, v124
	v_and_b32_e32 v153, 0xffff0000, v124
	v_lshlrev_b32_e32 v154, 16, v125
	v_and_b32_e32 v155, 0xffff0000, v125
	v_lshlrev_b32_e32 v156, 16, v126
	v_and_b32_e32 v157, 0xffff0000, v126
	v_lshlrev_b32_e32 v158, 16, v127
	v_and_b32_e32 v159, 0xffff0000, v127
	v_pk_mul_f32 v[160:161], v[0:1], v[144:145]
	v_pk_mul_f32 v[162:163], v[8:9], v[152:153]
	v_pk_fma_f32 v[160:161], v[2:3], v[146:147], v[160:161]
	v_pk_fma_f32 v[162:163], v[10:11], v[154:155], v[162:163]
	v_pk_fma_f32 v[160:161], v[4:5], v[148:149], v[160:161]
	v_pk_fma_f32 v[162:163], v[12:13], v[156:157], v[162:163]
	v_pk_fma_f32 v[160:161], v[6:7], v[150:151], v[160:161]
	v_pk_fma_f32 v[162:163], v[14:15], v[158:159], v[162:163]
	v_pk_add_f32 v[160:161], v[160:161], v[162:163]
	s_nop 0
	v_add_f32_e32 v169, v160, v161
	v_pk_mul_f32 v[160:161], v[16:17], v[144:145]
	v_pk_mul_f32 v[162:163], v[24:25], v[152:153]
	v_pk_fma_f32 v[160:161], v[18:19], v[146:147], v[160:161]
	v_pk_fma_f32 v[162:163], v[26:27], v[154:155], v[162:163]
	v_pk_fma_f32 v[160:161], v[20:21], v[148:149], v[160:161]
	v_pk_fma_f32 v[162:163], v[28:29], v[156:157], v[162:163]
	v_pk_fma_f32 v[160:161], v[22:23], v[150:151], v[160:161]
	v_pk_fma_f32 v[162:163], v[30:31], v[158:159], v[162:163]
	v_pk_add_f32 v[160:161], v[160:161], v[162:163]
	s_nop 0
	v_add_f32_e32 v170, v160, v161
	v_pk_mul_f32 v[160:161], v[32:33], v[144:145]
	v_pk_mul_f32 v[162:163], v[40:41], v[152:153]
	v_pk_fma_f32 v[160:161], v[34:35], v[146:147], v[160:161]
	v_pk_fma_f32 v[162:163], v[42:43], v[154:155], v[162:163]
	v_pk_fma_f32 v[160:161], v[36:37], v[148:149], v[160:161]
	v_pk_fma_f32 v[162:163], v[44:45], v[156:157], v[162:163]
	v_pk_fma_f32 v[160:161], v[38:39], v[150:151], v[160:161]
	v_pk_fma_f32 v[162:163], v[46:47], v[158:159], v[162:163]
	v_pk_add_f32 v[160:161], v[160:161], v[162:163]
	s_nop 0
	v_add_f32_e32 v171, v160, v161
	v_pk_mul_f32 v[160:161], v[48:49], v[144:145]
	v_pk_mul_f32 v[162:163], v[56:57], v[152:153]
	v_pk_fma_f32 v[160:161], v[50:51], v[146:147], v[160:161]
	v_pk_fma_f32 v[162:163], v[58:59], v[154:155], v[162:163]
	v_pk_fma_f32 v[160:161], v[52:53], v[148:149], v[160:161]
	v_pk_fma_f32 v[162:163], v[60:61], v[156:157], v[162:163]
	v_pk_fma_f32 v[160:161], v[54:55], v[150:151], v[160:161]
	v_pk_fma_f32 v[162:163], v[62:63], v[158:159], v[162:163]
	v_pk_add_f32 v[160:161], v[160:161], v[162:163]
	s_nop 0
	v_add_f32_e32 v172, v160, v161
	v_pk_mul_f32 v[160:161], v[64:65], v[144:145]
	v_pk_mul_f32 v[162:163], v[72:73], v[152:153]
	v_pk_fma_f32 v[160:161], v[66:67], v[146:147], v[160:161]
	v_pk_fma_f32 v[162:163], v[74:75], v[154:155], v[162:163]
	v_pk_fma_f32 v[160:161], v[68:69], v[148:149], v[160:161]
	v_pk_fma_f32 v[162:163], v[76:77], v[156:157], v[162:163]
	v_pk_fma_f32 v[160:161], v[70:71], v[150:151], v[160:161]
	v_pk_fma_f32 v[162:163], v[78:79], v[158:159], v[162:163]
	v_pk_add_f32 v[160:161], v[160:161], v[162:163]
	s_nop 0
	v_add_f32_e32 v173, v160, v161
	s_nop 1
	v_permlane32_swap_b32_e32 v164, v169
	v_permlane32_swap_b32_e32 v165, v170
	v_permlane32_swap_b32_e32 v166, v171
	v_permlane32_swap_b32_e32 v167, v172
	v_permlane32_swap_b32_e32 v168, v173
	s_nop 1
	v_add_f32_e32 v88, v164, v169
	v_add_f32_e32 v89, v165, v170
	v_add_f32_e32 v90, v166, v171
	v_add_f32_e32 v91, v167, v172
	v_add_f32_e32 v92, v168, v173
	s_waitcnt vmcnt(4)
	v_lshlrev_b32_e32 v144, 16, v96
	v_and_b32_e32 v145, 0xffff0000, v96
	v_lshlrev_b32_e32 v146, 16, v97
	v_and_b32_e32 v147, 0xffff0000, v97
	v_lshlrev_b32_e32 v148, 16, v98
	v_and_b32_e32 v149, 0xffff0000, v98
	v_lshlrev_b32_e32 v150, 16, v99
	v_and_b32_e32 v151, 0xffff0000, v99
	v_lshlrev_b32_e32 v152, 16, v100
	v_and_b32_e32 v153, 0xffff0000, v100
	v_lshlrev_b32_e32 v154, 16, v101
	v_and_b32_e32 v155, 0xffff0000, v101
	v_lshlrev_b32_e32 v156, 16, v102
	v_and_b32_e32 v157, 0xffff0000, v102
	v_lshlrev_b32_e32 v158, 16, v103
	v_and_b32_e32 v159, 0xffff0000, v103
	v_pk_mul_f32 v[160:161], v[0:1], v[144:145]
	v_pk_mul_f32 v[162:163], v[8:9], v[152:153]
	v_pk_fma_f32 v[160:161], v[2:3], v[146:147], v[160:161]
	v_pk_fma_f32 v[162:163], v[10:11], v[154:155], v[162:163]
	v_pk_fma_f32 v[160:161], v[4:5], v[148:149], v[160:161]
	v_pk_fma_f32 v[162:163], v[12:13], v[156:157], v[162:163]
	v_pk_fma_f32 v[160:161], v[6:7], v[150:151], v[160:161]
	v_pk_fma_f32 v[162:163], v[14:15], v[158:159], v[162:163]
	v_pk_add_f32 v[160:161], v[160:161], v[162:163]
	s_nop 0
	v_add_f32_e32 v164, v160, v161
	v_pk_mul_f32 v[160:161], v[16:17], v[144:145]
	v_pk_mul_f32 v[162:163], v[24:25], v[152:153]
	v_pk_fma_f32 v[160:161], v[18:19], v[146:147], v[160:161]
	v_pk_fma_f32 v[162:163], v[26:27], v[154:155], v[162:163]
	v_pk_fma_f32 v[160:161], v[20:21], v[148:149], v[160:161]
	v_pk_fma_f32 v[162:163], v[28:29], v[156:157], v[162:163]
	v_pk_fma_f32 v[160:161], v[22:23], v[150:151], v[160:161]
	v_pk_fma_f32 v[162:163], v[30:31], v[158:159], v[162:163]
	v_pk_add_f32 v[160:161], v[160:161], v[162:163]
	s_nop 0
	v_add_f32_e32 v165, v160, v161
	v_pk_mul_f32 v[160:161], v[32:33], v[144:145]
	v_pk_mul_f32 v[162:163], v[40:41], v[152:153]
	v_pk_fma_f32 v[160:161], v[34:35], v[146:147], v[160:161]
	v_pk_fma_f32 v[162:163], v[42:43], v[154:155], v[162:163]
	v_pk_fma_f32 v[160:161], v[36:37], v[148:149], v[160:161]
	v_pk_fma_f32 v[162:163], v[44:45], v[156:157], v[162:163]
	v_pk_fma_f32 v[160:161], v[38:39], v[150:151], v[160:161]
	v_pk_fma_f32 v[162:163], v[46:47], v[158:159], v[162:163]
	v_pk_add_f32 v[160:161], v[160:161], v[162:163]
	s_nop 0
	v_add_f32_e32 v166, v160, v161
	v_pk_mul_f32 v[160:161], v[48:49], v[144:145]
	v_pk_mul_f32 v[162:163], v[56:57], v[152:153]
	v_pk_fma_f32 v[160:161], v[50:51], v[146:147], v[160:161]
	v_pk_fma_f32 v[162:163], v[58:59], v[154:155], v[162:163]
	v_pk_fma_f32 v[160:161], v[52:53], v[148:149], v[160:161]
	v_pk_fma_f32 v[162:163], v[60:61], v[156:157], v[162:163]
	v_pk_fma_f32 v[160:161], v[54:55], v[150:151], v[160:161]
	v_pk_fma_f32 v[162:163], v[62:63], v[158:159], v[162:163]
	v_pk_add_f32 v[160:161], v[160:161], v[162:163]
	s_nop 0
	v_add_f32_e32 v167, v160, v161
	v_pk_mul_f32 v[160:161], v[64:65], v[144:145]
	v_pk_mul_f32 v[162:163], v[72:73], v[152:153]
	v_pk_fma_f32 v[160:161], v[66:67], v[146:147], v[160:161]
	v_pk_fma_f32 v[162:163], v[74:75], v[154:155], v[162:163]
	v_pk_fma_f32 v[160:161], v[68:69], v[148:149], v[160:161]
	v_pk_fma_f32 v[162:163], v[76:77], v[156:157], v[162:163]
	v_pk_fma_f32 v[160:161], v[70:71], v[150:151], v[160:161]
	v_pk_fma_f32 v[162:163], v[78:79], v[158:159], v[162:163]
	v_pk_add_f32 v[160:161], v[160:161], v[162:163]
	s_nop 0
	v_add_f32_e32 v168, v160, v161
	v_lshlrev_b32_e32 v144, 16, v128
	v_and_b32_e32 v145, 0xffff0000, v128
	v_lshlrev_b32_e32 v146, 16, v129
	v_and_b32_e32 v147, 0xffff0000, v129
	v_lshlrev_b32_e32 v148, 16, v130
	v_and_b32_e32 v149, 0xffff0000, v130
	v_lshlrev_b32_e32 v150, 16, v131
	v_and_b32_e32 v151, 0xffff0000, v131
	v_lshlrev_b32_e32 v152, 16, v132
	v_and_b32_e32 v153, 0xffff0000, v132
	v_lshlrev_b32_e32 v154, 16, v133
	v_and_b32_e32 v155, 0xffff0000, v133
	v_lshlrev_b32_e32 v156, 16, v134
	v_and_b32_e32 v157, 0xffff0000, v134
	v_lshlrev_b32_e32 v158, 16, v135
	v_and_b32_e32 v159, 0xffff0000, v135
	v_pk_mul_f32 v[160:161], v[0:1], v[144:145]
	v_pk_mul_f32 v[162:163], v[8:9], v[152:153]
	v_pk_fma_f32 v[160:161], v[2:3], v[146:147], v[160:161]
	v_pk_fma_f32 v[162:163], v[10:11], v[154:155], v[162:163]
	v_pk_fma_f32 v[160:161], v[4:5], v[148:149], v[160:161]
	v_pk_fma_f32 v[162:163], v[12:13], v[156:157], v[162:163]
	v_pk_fma_f32 v[160:161], v[6:7], v[150:151], v[160:161]
	v_pk_fma_f32 v[162:163], v[14:15], v[158:159], v[162:163]
	v_pk_add_f32 v[160:161], v[160:161], v[162:163]
	s_nop 0
	v_add_f32_e32 v169, v160, v161
	v_pk_mul_f32 v[160:161], v[16:17], v[144:145]
	v_pk_mul_f32 v[162:163], v[24:25], v[152:153]
	v_pk_fma_f32 v[160:161], v[18:19], v[146:147], v[160:161]
	v_pk_fma_f32 v[162:163], v[26:27], v[154:155], v[162:163]
	v_pk_fma_f32 v[160:161], v[20:21], v[148:149], v[160:161]
	v_pk_fma_f32 v[162:163], v[28:29], v[156:157], v[162:163]
	v_pk_fma_f32 v[160:161], v[22:23], v[150:151], v[160:161]
	v_pk_fma_f32 v[162:163], v[30:31], v[158:159], v[162:163]
	v_pk_add_f32 v[160:161], v[160:161], v[162:163]
	s_nop 0
	v_add_f32_e32 v170, v160, v161
	v_pk_mul_f32 v[160:161], v[32:33], v[144:145]
	v_pk_mul_f32 v[162:163], v[40:41], v[152:153]
	v_pk_fma_f32 v[160:161], v[34:35], v[146:147], v[160:161]
	v_pk_fma_f32 v[162:163], v[42:43], v[154:155], v[162:163]
	v_pk_fma_f32 v[160:161], v[36:37], v[148:149], v[160:161]
	v_pk_fma_f32 v[162:163], v[44:45], v[156:157], v[162:163]
	v_pk_fma_f32 v[160:161], v[38:39], v[150:151], v[160:161]
	v_pk_fma_f32 v[162:163], v[46:47], v[158:159], v[162:163]
	v_pk_add_f32 v[160:161], v[160:161], v[162:163]
	s_nop 0
	v_add_f32_e32 v171, v160, v161
	v_pk_mul_f32 v[160:161], v[48:49], v[144:145]
	v_pk_mul_f32 v[162:163], v[56:57], v[152:153]
	v_pk_fma_f32 v[160:161], v[50:51], v[146:147], v[160:161]
	v_pk_fma_f32 v[162:163], v[58:59], v[154:155], v[162:163]
	v_pk_fma_f32 v[160:161], v[52:53], v[148:149], v[160:161]
	v_pk_fma_f32 v[162:163], v[60:61], v[156:157], v[162:163]
	v_pk_fma_f32 v[160:161], v[54:55], v[150:151], v[160:161]
	v_pk_fma_f32 v[162:163], v[62:63], v[158:159], v[162:163]
	v_pk_add_f32 v[160:161], v[160:161], v[162:163]
	s_nop 0
	v_add_f32_e32 v172, v160, v161
	v_pk_mul_f32 v[160:161], v[64:65], v[144:145]
	v_pk_mul_f32 v[162:163], v[72:73], v[152:153]
	v_pk_fma_f32 v[160:161], v[66:67], v[146:147], v[160:161]
	v_pk_fma_f32 v[162:163], v[74:75], v[154:155], v[162:163]
	v_pk_fma_f32 v[160:161], v[68:69], v[148:149], v[160:161]
	v_pk_fma_f32 v[162:163], v[76:77], v[156:157], v[162:163]
	v_pk_fma_f32 v[160:161], v[70:71], v[150:151], v[160:161]
	v_pk_fma_f32 v[162:163], v[78:79], v[158:159], v[162:163]
	v_pk_add_f32 v[160:161], v[160:161], v[162:163]
	s_nop 0
	v_add_f32_e32 v173, v160, v161
	s_nop 1
	v_permlane32_swap_b32_e32 v164, v169
	v_permlane32_swap_b32_e32 v165, v170
	v_permlane32_swap_b32_e32 v166, v171
	v_permlane32_swap_b32_e32 v167, v172
	v_permlane32_swap_b32_e32 v168, v173
	s_nop 1
	v_add_f32_e32 v96, v164, v169
	v_add_f32_e32 v97, v165, v170
	v_add_f32_e32 v98, v166, v171
	v_add_f32_e32 v99, v167, v172
	v_add_f32_e32 v100, v168, v173
	s_waitcnt vmcnt(0)
	v_lshlrev_b32_e32 v144, 16, v104
	v_and_b32_e32 v145, 0xffff0000, v104
	v_lshlrev_b32_e32 v146, 16, v105
	v_and_b32_e32 v147, 0xffff0000, v105
	v_lshlrev_b32_e32 v148, 16, v106
	v_and_b32_e32 v149, 0xffff0000, v106
	v_lshlrev_b32_e32 v150, 16, v107
	v_and_b32_e32 v151, 0xffff0000, v107
	v_lshlrev_b32_e32 v152, 16, v108
	v_and_b32_e32 v153, 0xffff0000, v108
	v_lshlrev_b32_e32 v154, 16, v109
	v_and_b32_e32 v155, 0xffff0000, v109
	v_lshlrev_b32_e32 v156, 16, v110
	v_and_b32_e32 v157, 0xffff0000, v110
	v_lshlrev_b32_e32 v158, 16, v111
	v_and_b32_e32 v159, 0xffff0000, v111
	v_pk_mul_f32 v[160:161], v[0:1], v[144:145]
	v_pk_mul_f32 v[162:163], v[8:9], v[152:153]
	v_pk_fma_f32 v[160:161], v[2:3], v[146:147], v[160:161]
	v_pk_fma_f32 v[162:163], v[10:11], v[154:155], v[162:163]
	v_pk_fma_f32 v[160:161], v[4:5], v[148:149], v[160:161]
	v_pk_fma_f32 v[162:163], v[12:13], v[156:157], v[162:163]
	v_pk_fma_f32 v[160:161], v[6:7], v[150:151], v[160:161]
	v_pk_fma_f32 v[162:163], v[14:15], v[158:159], v[162:163]
	v_pk_add_f32 v[160:161], v[160:161], v[162:163]
	s_nop 0
	v_add_f32_e32 v164, v160, v161
	v_pk_mul_f32 v[160:161], v[16:17], v[144:145]
	v_pk_mul_f32 v[162:163], v[24:25], v[152:153]
	v_pk_fma_f32 v[160:161], v[18:19], v[146:147], v[160:161]
	v_pk_fma_f32 v[162:163], v[26:27], v[154:155], v[162:163]
	v_pk_fma_f32 v[160:161], v[20:21], v[148:149], v[160:161]
	v_pk_fma_f32 v[162:163], v[28:29], v[156:157], v[162:163]
	v_pk_fma_f32 v[160:161], v[22:23], v[150:151], v[160:161]
	v_pk_fma_f32 v[162:163], v[30:31], v[158:159], v[162:163]
	v_pk_add_f32 v[160:161], v[160:161], v[162:163]
	s_nop 0
	v_add_f32_e32 v165, v160, v161
	v_pk_mul_f32 v[160:161], v[32:33], v[144:145]
	v_pk_mul_f32 v[162:163], v[40:41], v[152:153]
	v_pk_fma_f32 v[160:161], v[34:35], v[146:147], v[160:161]
	v_pk_fma_f32 v[162:163], v[42:43], v[154:155], v[162:163]
	v_pk_fma_f32 v[160:161], v[36:37], v[148:149], v[160:161]
	v_pk_fma_f32 v[162:163], v[44:45], v[156:157], v[162:163]
	v_pk_fma_f32 v[160:161], v[38:39], v[150:151], v[160:161]
	v_pk_fma_f32 v[162:163], v[46:47], v[158:159], v[162:163]
	v_pk_add_f32 v[160:161], v[160:161], v[162:163]
	s_nop 0
	v_add_f32_e32 v166, v160, v161
	v_pk_mul_f32 v[160:161], v[48:49], v[144:145]
	v_pk_mul_f32 v[162:163], v[56:57], v[152:153]
	v_pk_fma_f32 v[160:161], v[50:51], v[146:147], v[160:161]
	v_pk_fma_f32 v[162:163], v[58:59], v[154:155], v[162:163]
	v_pk_fma_f32 v[160:161], v[52:53], v[148:149], v[160:161]
	v_pk_fma_f32 v[162:163], v[60:61], v[156:157], v[162:163]
	v_pk_fma_f32 v[160:161], v[54:55], v[150:151], v[160:161]
	v_pk_fma_f32 v[162:163], v[62:63], v[158:159], v[162:163]
	v_pk_add_f32 v[160:161], v[160:161], v[162:163]
	s_nop 0
	v_add_f32_e32 v167, v160, v161
	v_pk_mul_f32 v[160:161], v[64:65], v[144:145]
	v_pk_mul_f32 v[162:163], v[72:73], v[152:153]
	v_pk_fma_f32 v[160:161], v[66:67], v[146:147], v[160:161]
	v_pk_fma_f32 v[162:163], v[74:75], v[154:155], v[162:163]
	v_pk_fma_f32 v[160:161], v[68:69], v[148:149], v[160:161]
	v_pk_fma_f32 v[162:163], v[76:77], v[156:157], v[162:163]
	v_pk_fma_f32 v[160:161], v[70:71], v[150:151], v[160:161]
	v_pk_fma_f32 v[162:163], v[78:79], v[158:159], v[162:163]
	v_pk_add_f32 v[160:161], v[160:161], v[162:163]
	s_nop 0
	v_add_f32_e32 v168, v160, v161
	v_lshlrev_b32_e32 v144, 16, v136
	v_and_b32_e32 v145, 0xffff0000, v136
	v_lshlrev_b32_e32 v146, 16, v137
	v_and_b32_e32 v147, 0xffff0000, v137
	v_lshlrev_b32_e32 v148, 16, v138
	v_and_b32_e32 v149, 0xffff0000, v138
	v_lshlrev_b32_e32 v150, 16, v139
	v_and_b32_e32 v151, 0xffff0000, v139
	v_lshlrev_b32_e32 v152, 16, v140
	v_and_b32_e32 v153, 0xffff0000, v140
	v_lshlrev_b32_e32 v154, 16, v141
	v_and_b32_e32 v155, 0xffff0000, v141
	v_lshlrev_b32_e32 v156, 16, v142
	v_and_b32_e32 v157, 0xffff0000, v142
	v_lshlrev_b32_e32 v158, 16, v143
	v_and_b32_e32 v159, 0xffff0000, v143
	v_pk_mul_f32 v[160:161], v[0:1], v[144:145]
	v_pk_mul_f32 v[162:163], v[8:9], v[152:153]
	v_pk_fma_f32 v[160:161], v[2:3], v[146:147], v[160:161]
	v_pk_fma_f32 v[162:163], v[10:11], v[154:155], v[162:163]
	v_pk_fma_f32 v[160:161], v[4:5], v[148:149], v[160:161]
	v_pk_fma_f32 v[162:163], v[12:13], v[156:157], v[162:163]
	v_pk_fma_f32 v[160:161], v[6:7], v[150:151], v[160:161]
	v_pk_fma_f32 v[162:163], v[14:15], v[158:159], v[162:163]
	v_pk_add_f32 v[160:161], v[160:161], v[162:163]
	s_nop 0
	v_add_f32_e32 v169, v160, v161
	v_pk_mul_f32 v[160:161], v[16:17], v[144:145]
	v_pk_mul_f32 v[162:163], v[24:25], v[152:153]
	v_pk_fma_f32 v[160:161], v[18:19], v[146:147], v[160:161]
	v_pk_fma_f32 v[162:163], v[26:27], v[154:155], v[162:163]
	v_pk_fma_f32 v[160:161], v[20:21], v[148:149], v[160:161]
	v_pk_fma_f32 v[162:163], v[28:29], v[156:157], v[162:163]
	v_pk_fma_f32 v[160:161], v[22:23], v[150:151], v[160:161]
	v_pk_fma_f32 v[162:163], v[30:31], v[158:159], v[162:163]
	v_pk_add_f32 v[160:161], v[160:161], v[162:163]
	s_nop 0
	v_add_f32_e32 v170, v160, v161
	v_pk_mul_f32 v[160:161], v[32:33], v[144:145]
	v_pk_mul_f32 v[162:163], v[40:41], v[152:153]
	v_pk_fma_f32 v[160:161], v[34:35], v[146:147], v[160:161]
	v_pk_fma_f32 v[162:163], v[42:43], v[154:155], v[162:163]
	v_pk_fma_f32 v[160:161], v[36:37], v[148:149], v[160:161]
	v_pk_fma_f32 v[162:163], v[44:45], v[156:157], v[162:163]
	v_pk_fma_f32 v[160:161], v[38:39], v[150:151], v[160:161]
	v_pk_fma_f32 v[162:163], v[46:47], v[158:159], v[162:163]
	v_pk_add_f32 v[160:161], v[160:161], v[162:163]
	s_nop 0
	v_add_f32_e32 v171, v160, v161
	v_pk_mul_f32 v[160:161], v[48:49], v[144:145]
	v_pk_mul_f32 v[162:163], v[56:57], v[152:153]
	v_pk_fma_f32 v[160:161], v[50:51], v[146:147], v[160:161]
	v_pk_fma_f32 v[162:163], v[58:59], v[154:155], v[162:163]
	v_pk_fma_f32 v[160:161], v[52:53], v[148:149], v[160:161]
	v_pk_fma_f32 v[162:163], v[60:61], v[156:157], v[162:163]
	v_pk_fma_f32 v[160:161], v[54:55], v[150:151], v[160:161]
	v_pk_fma_f32 v[162:163], v[62:63], v[158:159], v[162:163]
	v_pk_add_f32 v[160:161], v[160:161], v[162:163]
	s_nop 0
	v_add_f32_e32 v172, v160, v161
	v_pk_mul_f32 v[160:161], v[64:65], v[144:145]
	v_pk_mul_f32 v[162:163], v[72:73], v[152:153]
	v_pk_fma_f32 v[160:161], v[66:67], v[146:147], v[160:161]
	v_pk_fma_f32 v[162:163], v[74:75], v[154:155], v[162:163]
	v_pk_fma_f32 v[160:161], v[68:69], v[148:149], v[160:161]
	v_pk_fma_f32 v[162:163], v[76:77], v[156:157], v[162:163]
	v_pk_fma_f32 v[160:161], v[70:71], v[150:151], v[160:161]
	v_pk_fma_f32 v[162:163], v[78:79], v[158:159], v[162:163]
	v_pk_add_f32 v[160:161], v[160:161], v[162:163]
	s_nop 0
	v_add_f32_e32 v173, v160, v161
	s_nop 1
	v_permlane32_swap_b32_e32 v164, v169
	v_permlane32_swap_b32_e32 v165, v170
	v_permlane32_swap_b32_e32 v166, v171
	v_permlane32_swap_b32_e32 v167, v172
	v_permlane32_swap_b32_e32 v168, v173
	s_nop 1
	v_add_f32_e32 v104, v164, v169
	v_add_f32_e32 v105, v165, v170
	v_add_f32_e32 v106, v166, v171
	v_add_f32_e32 v107, v167, v172
	v_add_f32_e32 v108, v168, v173
	s_nop 1
	v_permlane16_swap_b32_e32 v80, v96
	v_permlane16_swap_b32_e32 v81, v97
	v_permlane16_swap_b32_e32 v82, v98
	v_permlane16_swap_b32_e32 v83, v99
	v_permlane16_swap_b32_e32 v84, v100
	v_permlane16_swap_b32_e32 v88, v104
	v_permlane16_swap_b32_e32 v89, v105
	v_permlane16_swap_b32_e32 v90, v106
	v_permlane16_swap_b32_e32 v91, v107
	v_permlane16_swap_b32_e32 v92, v108
	s_nop 1
	v_add_f32_e32 v80, v80, v96
	v_add_f32_e32 v81, v81, v97
	v_add_f32_e32 v82, v82, v98
	v_add_f32_e32 v83, v83, v99
	v_add_f32_e32 v84, v84, v100
	v_add_f32_e32 v88, v88, v104
	v_add_f32_e32 v89, v89, v105
	v_add_f32_e32 v90, v90, v106
	v_add_f32_e32 v91, v91, v107
	v_add_f32_e32 v92, v92, v108
	s_nop 1
	v_add_f32_dpp v80, v80, v80 quad_perm:[1,0,3,2] row_mask:0xf bank_mask:0xf
	v_add_f32_dpp v81, v81, v81 quad_perm:[1,0,3,2] row_mask:0xf bank_mask:0xf
	v_add_f32_dpp v82, v82, v82 quad_perm:[1,0,3,2] row_mask:0xf bank_mask:0xf
	v_add_f32_dpp v83, v83, v83 quad_perm:[1,0,3,2] row_mask:0xf bank_mask:0xf
	v_add_f32_dpp v84, v84, v84 quad_perm:[1,0,3,2] row_mask:0xf bank_mask:0xf
	v_add_f32_dpp v88, v88, v88 quad_perm:[1,0,3,2] row_mask:0xf bank_mask:0xf
	v_add_f32_dpp v89, v89, v89 quad_perm:[1,0,3,2] row_mask:0xf bank_mask:0xf
	v_add_f32_dpp v90, v90, v90 quad_perm:[1,0,3,2] row_mask:0xf bank_mask:0xf
	v_add_f32_dpp v91, v91, v91 quad_perm:[1,0,3,2] row_mask:0xf bank_mask:0xf
	v_add_f32_dpp v92, v92, v92 quad_perm:[1,0,3,2] row_mask:0xf bank_mask:0xf
	s_nop 1
	v_add_f32_dpp v80, v80, v80 quad_perm:[2,3,0,1] row_mask:0xf bank_mask:0xf
	v_add_f32_dpp v81, v81, v81 quad_perm:[2,3,0,1] row_mask:0xf bank_mask:0xf
	v_add_f32_dpp v82, v82, v82 quad_perm:[2,3,0,1] row_mask:0xf bank_mask:0xf
	v_add_f32_dpp v83, v83, v83 quad_perm:[2,3,0,1] row_mask:0xf bank_mask:0xf
	v_add_f32_dpp v84, v84, v84 quad_perm:[2,3,0,1] row_mask:0xf bank_mask:0xf
	v_add_f32_dpp v88, v88, v88 quad_perm:[2,3,0,1] row_mask:0xf bank_mask:0xf
	v_add_f32_dpp v89, v89, v89 quad_perm:[2,3,0,1] row_mask:0xf bank_mask:0xf
	v_add_f32_dpp v90, v90, v90 quad_perm:[2,3,0,1] row_mask:0xf bank_mask:0xf
	v_add_f32_dpp v91, v91, v91 quad_perm:[2,3,0,1] row_mask:0xf bank_mask:0xf
	v_add_f32_dpp v92, v92, v92 quad_perm:[2,3,0,1] row_mask:0xf bank_mask:0xf
	s_nop 1
	v_add_f32_dpp v80, v80, v80 row_ror:4 row_mask:0xf bank_mask:0xf
	v_add_f32_dpp v81, v81, v81 row_ror:4 row_mask:0xf bank_mask:0xf
	v_add_f32_dpp v82, v82, v82 row_ror:4 row_mask:0xf bank_mask:0xf
	v_add_f32_dpp v83, v83, v83 row_ror:4 row_mask:0xf bank_mask:0xf
	v_add_f32_dpp v84, v84, v84 row_ror:4 row_mask:0xf bank_mask:0xf
	v_add_f32_dpp v88, v88, v88 row_ror:4 row_mask:0xf bank_mask:0xf
	v_add_f32_dpp v89, v89, v89 row_ror:4 row_mask:0xf bank_mask:0xf
	v_add_f32_dpp v90, v90, v90 row_ror:4 row_mask:0xf bank_mask:0xf
	v_add_f32_dpp v91, v91, v91 row_ror:4 row_mask:0xf bank_mask:0xf
	v_add_f32_dpp v92, v92, v92 row_ror:4 row_mask:0xf bank_mask:0xf
	s_nop 1
	v_add_f32_dpp v80, v80, v80 row_ror:8 row_mask:0xf bank_mask:0xf
	v_add_f32_dpp v81, v81, v81 row_ror:8 row_mask:0xf bank_mask:0xf
	v_add_f32_dpp v82, v82, v82 row_ror:8 row_mask:0xf bank_mask:0xf
	v_add_f32_dpp v83, v83, v83 row_ror:8 row_mask:0xf bank_mask:0xf
	v_add_f32_dpp v84, v84, v84 row_ror:8 row_mask:0xf bank_mask:0xf
	v_add_f32_dpp v88, v88, v88 row_ror:8 row_mask:0xf bank_mask:0xf
	v_add_f32_dpp v89, v89, v89 row_ror:8 row_mask:0xf bank_mask:0xf
	v_add_f32_dpp v90, v90, v90 row_ror:8 row_mask:0xf bank_mask:0xf
	v_add_f32_dpp v91, v91, v91 row_ror:8 row_mask:0xf bank_mask:0xf
	v_add_f32_dpp v92, v92, v92 row_ror:8 row_mask:0xf bank_mask:0xf
	s_nop 1
	v_and_b32_e32 v160, 63, v229
	v_lshrrev_b32_e32 v161, 6, v229
	v_lshrrev_b32_e32 v162, 4, v160
	v_lshlrev_b32_e32 v162, 1, v162
	v_lshl_add_u32 v162, v161, 3, v162
	s_lshl_b32 s52, s54, 5
	v_add_u32_e32 v162, s52, v162
	s_cmp_eq_u32 s48, 0
	s_cbranch_scc1 .Lbias_col0
	v_lshrrev_b32_e32 v163, 8, v162
	v_lshlrev_b32_e32 v163, 7, v163
	v_and_b32_e32 v164, 0x7f, v162
	v_add_u32_e32 v163, v163, v164
	v_bfe_u32 v164, v162, 7, 1
	v_mul_u32_u24_e32 v164, 0xb00, v164
	v_add_u32_e32 v162, v163, v164
.Lbias_col0:
	v_lshlrev_b32_e32 v162, 2, v162
	v_add_u32_e32 v163, s46, v162
	v_add_u32_e32 v164, s46, v163
	v_add_u32_e32 v165, s46, v164
	v_add_u32_e32 v166, s46, v165
	v_and_b32_e32 v160, 15, v160
	v_cmp_eq_u32_e64 s[52:53], 0, v160
	s_nop 4
	s_and_b64 exec, exec, s[52:53]
	global_store_dword v162, v80, s[44:45]
	global_store_dword v162, v88, s[44:45] offset:4
	global_store_dword v163, v81, s[44:45]
	global_store_dword v163, v89, s[44:45] offset:4
	global_store_dword v164, v82, s[44:45]
	global_store_dword v164, v90, s[44:45] offset:4
	global_store_dword v165, v83, s[44:45]
	global_store_dword v165, v91, s[44:45] offset:4
	global_store_dword v166, v84, s[44:45]
	global_store_dword v166, v92, s[44:45] offset:4
	s_mov_b64 exec, s[50:51]
	s_add_i32 s54, s54, s70
	s_cmp_lt_i32 s54, s55
	s_cbranch_scc1 .Lbias_again
	v_mul_u32_u24_e32 v0, 0xc0, v228
	ds_read_b128 v[128:131], v0 offset:0
	ds_read_b128 v[132:135], v0 offset:16
	ds_read_b128 v[136:139], v0 offset:32
	ds_read_b128 v[140:143], v0 offset:48
	ds_read_b128 v[144:147], v0 offset:64
	ds_read_b128 v[148:151], v0 offset:80
	ds_read_b128 v[152:155], v0 offset:96
	ds_read_b128 v[156:159], v0 offset:112
	ds_read_b128 v[160:163], v0 offset:128
	ds_read_b128 v[164:167], v0 offset:144
	ds_read_b128 v[168:171], v0 offset:160
	ds_read_b128 v[172:175], v0 offset:176
	s_mov_b32 s28, s49
	v_readlane_b32 s40, v255, 42
	v_readlane_b32 s41, v255, 43
	v_readlane_b32 s42, v255, 44
	v_readlane_b32 s43, v255, 45
	v_readlane_b32 s44, v255, 46
	v_readlane_b32 s45, v255, 47
	v_readlane_b32 s46, v255, 48
	v_readlane_b32 s47, v255, 49
	v_readlane_b32 s48, v255, 50
	v_readlane_b32 s49, v255, 51
	v_readlane_b32 s50, v255, 52
	v_readlane_b32 s51, v255, 53
	v_readlane_b32 s52, v255, 54
	v_readlane_b32 s53, v255, 55
	v_readlane_b32 s54, v255, 56
	v_readlane_b32 s55, v255, 57
	s_waitcnt lgkmcnt(0)
	s_nop 3
	s_cmp_eq_u32 s28, 1
	s_cbranch_scc1 .Lbias_ret1
	s_cmp_eq_u32 s28, 2
	s_cbranch_scc1 .Lbias_ret2
	s_branch .Lbias_ret3
.LBB0_286:
	v_readlane_b32 s0, v255, 34
	s_nop 3
	s_cmpk_gt_i32 s0, 0xaf
	s_cbranch_scc1 .LBB0_291
	v_readlane_b32 s28, v255, 36
	s_nop 3
	s_lshl_b32 s28, s28, 8
	s_or_b32 s28, s28, s0
	s_or_b32 s28, s28, 0xa00
	s_branch .Lbias_task
.Lbias_ret2:
.LBB0_291:
	s_cmpk_gt_i32 s30, 0xff
	s_cbranch_scc1 .LBB0_385
	v_readlane_b32 s2, v255, 36
	s_lshl_b32 s0, s2, 3
	s_lshl_b32 s46, s90, 2
	s_add_i32 s47, s46, s0
	s_sub_i32 s33, 1, s90
	s_add_i32 s48, s47, -16
	s_cmp_eq_u32 s90, 0
	s_cselect_b64 s[36:37], -1, 0
	s_and_b64 s[0:1], s[36:37], exec
	s_movk_i32 s0, 0x500
	s_mul_i32 s33, s33, 0x12000
	s_cselect_b32 s49, s0, 0x700
	s_add_i32 s50, s69, 0x9000
	s_add_i32 s51, s69, 0x4800
	s_mov_b32 s52, s30
	s_mov_b32 s53, s30
	v_readlane_b32 s3, v255, 37
	s_branch .LBB0_294

.LBB0_558:
	s_nop 0
	v_readlane_b32 s0, v255, 39
	v_readlane_b32 s1, v255, 40
	s_and_b64 vcc, exec, s[0:1]
	s_cbranch_vccz .LBB0_677
	s_add_i32 s0, s74, 3
	s_cmp_lt_u32 s0, 11
	v_readlane_b32 s0, v255, 34
	s_cselect_b64 s[2:3], -1, 0
	s_cmpk_lt_i32 s0, 0x58
	s_cselect_b64 s[0:1], -1, 0
	s_and_b64 s[0:1], s[2:3], s[0:1]
	s_andn2_b64 vcc, exec, s[0:1]
	s_cbranch_vccnz .LBB0_564
	v_readlane_b32 s28, v255, 34
	s_nop 3
	s_or_b32 s28, s28, 0xd00
	s_branch .Lbias_task
.Lbias_ret3:
.LBB0_564:
	v_mov_b32_e32 v0, v228
	v_readlane_b32 s0, v255, 36
	v_bfe_i32 v4, v0, 27, 1
	v_lshlrev_b32_e32 v2, 4, v0
	v_lshrrev_b32_e32 v4, 22, v4
	v_add_u32_e32 v4, v2, v4
	v_and_b32_e32 v4, 0xfffffc00, v4
	v_sub_u32_e32 v4, v2, v4
	v_lshrrev_b32_e32 v5, 4, v4
	v_ashrrev_i32_e32 v3, 31, v0
	v_bitop3_b32 v4, v5, v4, 32 bitop3:0x6c
	v_lshrrev_b32_e32 v3, 26, v3
	v_ashrrev_i32_e32 v6, 31, v4
	v_add_u32_e32 v3, v0, v3
	v_lshrrev_b32_e32 v6, 26, v6
	v_readlane_b32 s1, v255, 37
	s_mov_b32 s28, s0
	v_readlane_b32 s36, v254, 57
	v_ashrrev_i32_e32 v3, 6, v3
	v_add_u32_e32 v6, v4, v6
	s_mul_i32 s1, s28, 0x580000
	v_readlane_b32 s44, v255, 1
	v_lshlrev_b32_e32 v5, 3, v3
	v_ashrrev_i32_e32 v7, 6, v6
	v_and_b32_e32 v6, 0xc0, v6
	s_mul_hi_i32 s0, s0, 0x580000
	v_readlane_b32 s45, v255, 2
	v_readlane_b32 s46, v255, 3
	s_add_u32 s33, s44, s1
	v_and_b32_e32 v5, -16, v5
	v_lshlrev_b32_e32 v3, 5, v3
	v_sub_u32_e32 v4, v4, v6
	s_addc_u32 s46, s45, s0
	s_mul_hi_i32 s0, s28, 0x1e000
	s_mul_i32 s1, s28, 0x1e000
	v_add_u32_e32 v5, v7, v5
	v_and_b32_e32 v3, 32, v3
	v_ashrrev_i16_sdwa v4, v249, sext(v4) dst_sel:DWORD dst_unused:UNUSED_PAD src0_sel:DWORD src1_sel:BYTE_0
	s_movk_i32 s28, 0xb00
	v_add_u32_sdwa v3, v3, sext(v4) dst_sel:DWORD dst_unused:UNUSED_PAD src0_sel:DWORD src1_sel:WORD_0
	v_mul_lo_u32 v4, v5, s28
	v_add_lshl_u32 v210, v3, v4, 1
	v_lshlrev_b32_e32 v4, 1, v5
	v_lshrrev_b32_e32 v6, 2, v5
	v_and_b32_e32 v7, 3, v7
	s_mov_b32 s29, 0xffffe0
	v_and_b32_e32 v4, 24, v4
	v_and_b32_e32 v6, 4, v6
	v_and_or_b32 v5, v5, s29, v7
	v_or3_b32 v4, v5, v6, v4
	v_mul_u32_u24_e32 v4, 0xb00, v4
	v_add_u32_e32 v2, 0x2000, v2
	v_add_lshl_u32 v212, v4, v3, 1
	v_ashrrev_i32_e32 v3, 31, v2
	v_lshrrev_b32_e32 v3, 22, v3
	v_add_u32_e32 v3, v2, v3
	v_ashrrev_i32_e32 v3, 10, v3
	v_mul_i32_i24_e32 v4, 0x400, v3
	v_sub_u32_e32 v2, v2, v4
	v_lshrrev_b32_e32 v4, 4, v2
	v_bitop3_b32 v2, v4, v2, 32 bitop3:0x6c
	v_ashrrev_i32_e32 v5, 31, v2
	v_readlane_b32 s50, v255, 7
	v_lshrrev_b32_e32 v5, 26, v5
	v_readlane_b32 s51, v255, 8
	s_add_u32 s1, s50, s1
	v_add_u32_e32 v5, v2, v5
	v_readlane_b32 s47, v255, 4
	s_addc_u32 s0, s51, s0
	v_lshlrev_b32_e32 v4, 3, v3
	v_ashrrev_i32_e32 v6, 6, v5
	v_and_b32_e32 v5, 0xc0, v5
	v_readlane_b32 s48, v255, 5
	s_add_u32 s47, s1, 0x5000
	v_and_b32_e32 v4, -16, v4
	v_lshlrev_b32_e32 v3, 5, v3
	v_sub_u32_e32 v2, v2, v5
	s_addc_u32 s48, s0, 0
	v_add_u32_e32 v4, v6, v4
	v_and_b32_e32 v3, 32, v3
	v_ashrrev_i16_sdwa v2, v249, sext(v2) dst_sel:DWORD dst_unused:UNUSED_PAD src0_sel:DWORD src1_sel:BYTE_0
	s_and_b64 s[0:1], s[2:3], exec
	v_add_u32_sdwa v2, v3, sext(v2) dst_sel:DWORD dst_unused:UNUSED_PAD src0_sel:DWORD src1_sel:WORD_0
	v_mul_lo_u32 v3, v4, s28
	v_readlane_b32 s0, v255, 12
	v_add_lshl_u32 v214, v2, v3, 1
	v_lshlrev_b32_e32 v3, 1, v4
	v_lshrrev_b32_e32 v5, 2, v4
	v_and_b32_e32 v6, 3, v6
	s_cselect_b32 s50, s0, 0
	v_readlane_b32 s0, v255, 11
	v_and_b32_e32 v3, 24, v3
	v_and_b32_e32 v5, 4, v5
	v_and_or_b32 v4, v4, s29, v6
	s_cselect_b32 s51, s0, 0
	v_readfirstlane_b32 s0, v0
	v_or3_b32 v3, v4, v5, v3
	s_ashr_i32 s1, s0, 6
	s_waitcnt lgkmcnt(0)
	v_bfe_u32 v1, v0, 4, 2
	v_mul_u32_u24_e32 v3, 0xb00, v3
	s_ashr_i32 s0, s0, 2
	v_add_lshl_u32 v216, v3, v2, 1
	v_and_b32_e32 v2, 15, v0
	s_andn2_b32 s0, s0, 63
	v_lshlrev_b32_e32 v4, 4, v1
	v_lshlrev_b32_e32 v0, 2, v0
	s_and_b32 s52, s1, 3
	v_or_b32_e32 v247, s0, v2
	v_lshl_or_b32 v2, v2, 6, v4
	s_lshl_b32 s0, s0, 7
	v_and_b32_e32 v0, 32, v0
	v_readlane_b32 s37, v254, 58
	v_readlane_b32 s49, v255, 6
	v_lshlrev_b32_e32 v3, 3, v1
	v_bitop3_b32 v4, v2, s0, v0 bitop3:0xde
	s_lshl_b32 s0, s52, 12
	s_mov_b32 s49, 0
	s_lshl_b32 s53, s1, 10
	v_lshl_or_b32 v230, s52, 5, v3
	v_bitop3_b32 v231, s0, v2, v0 bitop3:0xf6
	v_add_u32_e32 v245, 0x4000, v4
	v_add_u32_e32 v248, 0x8000, v4
	v_cmp_eq_u32_e64 s[36:37], 0, v1
	v_mov_b32_e32 v213, v201
	v_mov_b32_e32 v217, v201
	v_mov_b32_e32 v211, v201
	v_mov_b32_e32 v215, v201
	s_ashr_i32 s54, s30, 31
	v_readlane_b32 s38, v254, 59
	v_readlane_b32 s39, v254, 60
	v_readlane_b32 s40, v254, 61
	v_readlane_b32 s41, v254, 62
	v_readlane_b32 s42, v254, 63
	v_readlane_b32 s43, v255, 0
	s_branch .LBB0_567
